# stack26 + seam 3 (P3->P4) as an XCD-local barrier: P3 items handed out by the XCD-aware index so a bg's 16 producers are its 16 consumers on one XCD; start-up check falls back to the full barrier
# baseline (speedup 1.0000x reference)
.LBB0_7:
	s_lshr_b32 s98, s93, 5
	s_cmp_lg_u32 s98, s82
	s_cselect_b32 s98, 1, 0
	s_cmp_lg_u32 s79, 0x100
	s_cselect_b32 s99, 1, 0
	s_or_b32 s98, s98, s99
	s_cmp_eq_u32 s98, 0
	s_cbranch_scc1 .Lx3_chk_ok
	s_and_saveexec_b64 s[98:99], s[84:85]
	s_cbranch_execz .Lx3_chk_e
	v_mov_b32_e32 v248, 0x404
	v_mov_b32_e32 v249, 1
	global_atomic_add v248, v249, s[76:77]
.Lx3_chk_e:
	s_or_b64 exec, exec, s[98:99]
.Lx3_chk_ok:
	s_load_dwordx2 s[88:89], s[80:81], 0x90
	s_lshr_b32 s90, s83, 6
	v_and_b32_e32 v1, 63, v0
	s_waitcnt lgkmcnt(0)
	s_cmp_lt_i32 s88, 1
	s_cselect_b64 s[0:1], -1, 0
	s_cmp_gt_i32 s89, 0
	s_cselect_b64 s[2:3], -1, 0
	s_and_b64 s[2:3], s[0:1], s[2:3]
	s_andn2_b64 vcc, exec, s[2:3]
	s_cbranch_vccnz .LBB0_80
	s_load_dwordx8 s[8:15], s[80:81], 0x0
	s_lshl_b32 s0, s93, 3
	s_add_i32 s16, s0, s90
	s_lshl_b32 s18, s79, 3
	s_lshl_b32 s0, s93, 9
	s_lshl_b32 s6, s79, 9
	s_cmpk_gt_i32 s16, 0x267f
	s_cbranch_scc1 .LBB0_57
	v_lshlrev_b32_e32 v2, 2, v0
	v_and_b32_e32 v72, 60, v2
	v_lshlrev_b32_e32 v2, 3, v0
	v_and_b32_e32 v2, 56, v2
	v_lshlrev_b32_e32 v66, 1, v2
	v_mov_b32_e32 v67, 0
	s_mul_i32 s1, s90, 0x4100
	v_lshrrev_b32_e32 v74, 3, v1
	v_mul_u32_u24_e32 v6, 0x104, v2
	v_lshl_add_u64 v[2:3], s[76:77], 0, v[66:67]
	s_mov_b64 s[4:5], 0x10000
	s_add_i32 s1, s1, 0
	v_lshl_add_u64 v[68:69], v[2:3], 0, s[4:5]
	v_lshlrev_b32_e32 v2, 2, v74
	v_lshl_add_u32 v4, v72, 2, s1
	v_add3_u32 v75, s1, v6, v2
	s_lshl_b32 s1, s93, 8
	s_lshl_b32 s4, s90, 5
	v_lshrrev_b32_e32 v73, 4, v1
	s_add_i32 s1, s1, s4
	s_lshl_b32 s4, s90, 6
	v_mul_u32_u24_e32 v5, 0x104, v73
	s_add_i32 s17, s0, s4
	s_lshl_b32 s4, s93, 4
	s_lshl_b32 s5, s90, 1
	s_mov_b32 s21, 0
	v_or_b32_e32 v76, 8, v74
	v_or_b32_e32 v77, 16, v74
	v_or_b32_e32 v78, 24, v74
	v_or_b32_e32 v79, 32, v74
	v_or_b32_e32 v80, 40, v74
	v_or_b32_e32 v81, 48, v74
	v_or_b32_e32 v82, 56, v74
	s_lshl_b32 s7, s79, 8
	s_add_i32 s19, s4, s5
	s_lshl_b32 s24, s79, 4
	s_movk_i32 s25, 0x13ff
	s_movk_i32 s26, 0x4c30
	s_movk_i32 s27, 0x780
	s_movk_i32 s28, 0x1000
	s_movk_i32 s29, 0x1c30
	s_movk_i32 s30, 0x2c30
	v_add_u32_e32 v83, v4, v5
	s_mov_b32 s31, s16
	s_branch .LBB0_11

.LBB0_570:
	v_mov_b32_e32 v250, 1
	s_cmp_lt_i32 s88, 4
	s_cselect_b64 s[0:1], -1, 0
	s_and_b64 s[2:3], s[0:1], s[2:3]
	s_andn2_b64 vcc, exec, s[2:3]
	s_cbranch_vccnz .LBB0_586
	s_cmpk_gt_i32 s78, 0xff
	s_cbranch_scc1 .LBB0_586
	s_waitcnt vmcnt(0)
	v_and_b32_e32 v4, 0xff, v0
	v_lshl_add_u32 v8, v4, 6, 0
	v_mul_i32_i24_e32 v9, 0xffffffc4, v4
	v_mov_b32_e32 v5, 0
	v_lshlrev_b32_e32 v4, 1, v4
	v_lshl_add_u64 v[6:7], s[76:77], 0, v[4:5]
	v_or_b32_e32 v4, 0x200, v0
	s_load_dwordx2 s[6:7], s[80:81], 0x30
	s_load_dwordx2 s[8:9], s[80:81], 0x48
	v_lshrrev_b32_e32 v17, 8, v4
	v_or_b32_e32 v4, 0x600, v0
	v_lshrrev_b32_e32 v20, 8, v4
	v_or_b32_e32 v4, 0xa00, v0
	v_lshrrev_b32_e32 v10, 7, v0
	v_lshrrev_b32_e32 v23, 8, v4
	v_or_b32_e32 v4, 0xe00, v0
	s_movk_i32 s0, 0x100
	s_add_u32 s12, s76, 0x1ce33400
	v_lshrrev_b32_e32 v15, 8, v0
	v_lshrrev_b32_e32 v26, 8, v4
	v_lshl_add_u32 v4, v10, 4, 0
	v_cmp_gt_u32_e64 s[4:5], s0, v0
	s_mov_b32 s11, 0
	v_lshl_add_u32 v3, v0, 2, 0
	s_addc_u32 s13, s77, 0
	s_movk_i32 s0, 0x7f
	v_lshrrev_b32_e32 v2, 6, v0
	v_and_b32_e32 v14, 15, v0
	v_lshl_add_u32 v2, v2, 4, v14
	v_lshrrev_b32_e32 v14, 2, v0
	v_and_b32_e32 v14, 12, v14
	v_lshl_add_u32 v16, v15, 2, v8
	v_lshl_add_u32 v18, v17, 2, v8
	v_or_b32_e32 v19, 4, v15
	v_lshl_add_u32 v21, v20, 2, v8
	v_or_b32_e32 v22, 8, v15
	v_lshl_add_u32 v24, v23, 2, v8
	v_or_b32_e32 v25, 12, v15
	v_lshl_add_u32 v27, v26, 2, v8
	v_and_b32_e32 v28, 63, v0
	v_lshl_add_u32 v28, v28, 2, 0
	v_add_u32_e32 v28, 0x400, v28
	s_mov_b32 s1, 0x1bd33400
	v_lshlrev_b32_e32 v29, 2, v2
	v_lshl_add_u32 v29, v14, 7, v29
	s_mov_b32 s18, 0x200000
	s_mov_b32 s19, 0x400000
	s_mov_b32 s20, 0x600000
	s_movk_i32 s21, 0x1000
	s_mov_b32 s22, 0x1cd33400
	s_movk_i32 s23, 0x7e
	s_movk_i32 s24, 0x7d
	s_movk_i32 s25, 0x7c
	s_mov_b32 s26, s78
	s_cmp_lg_u32 s79, 0x100
	s_cbranch_scc1 .Lx3_item
	s_lshr_b32 s26, s93, 4
	s_lshl_b32 s26, s26, 3
	s_and_b32 s98, s93, 7
	s_or_b32 s26, s26, s98
	s_bfe_u32 s98, s93, 0x10003
	s_lshl_b32 s98, s98, 7
	s_or_b32 s26, s26, s98
.Lx3_item:
	v_mov_b32_e32 v251, 0x404
	global_load_dword v250, v251, s[76:77] sc1

.LBB0_586:
	s_cmp_gt_i32 s89, 4
	s_cselect_b64 s[4:5], -1, 0
	s_and_b64 s[0:1], s[2:3], s[4:5]
	s_andn2_b64 vcc, exec, s[0:1]
	s_cbranch_vccnz .LBB0_640
	s_waitcnt vmcnt(0)
	s_waitcnt vmcnt(0)
	s_barrier
	s_and_saveexec_b64 s[2:3], s[84:85]
	s_cbranch_execz .LBB0_639
	v_readfirstlane_b32 s98, v250
	s_cmp_lg_u32 s98, 0
	s_cbranch_scc1 .Lx3_full
	v_mov_b32_e32 v248, 0x23e20
	ds_read_b32 v249, v248
	ds_read_b32 v250, v248 offset:4
	v_mov_b32_e32 v251, s82
	v_lshlrev_b32_e32 v251, 8, v251
	v_add_u32_e32 v251, 0x1400, v251
	v_mov_b32_e32 v252, 1
	global_atomic_add v253, v251, v252, s[76:77] sc0
	s_waitcnt lgkmcnt(0)
	v_cvt_f32_u32_e32 v254, v249
	v_rcp_iflag_f32_e32 v254, v254
	v_sub_u32_e32 v255, 0, v249
	s_nop 0
	v_mul_f32_e32 v254, 0x4f7ffffe, v254
	v_cvt_u32_f32_e32 v254, v254
	v_mul_lo_u32 v255, v255, v254
	v_mul_hi_u32 v255, v254, v255
	v_add_u32_e32 v254, v254, v255
	s_waitcnt vmcnt(0)
	v_mul_hi_u32 v255, v253, v254
	v_mul_lo_u32 v252, v255, v249
	v_sub_u32_e32 v252, v253, v252
	v_add_u32_e32 v248, 1, v255
	v_cmp_ge_u32_e32 vcc, v252, v249
	s_nop 1
	v_cndmask_b32_e32 v255, v255, v248, vcc
	v_sub_u32_e32 v248, v252, v249
	v_cndmask_b32_e32 v252, v252, v248, vcc
	v_add_u32_e32 v248, 1, v255
	v_cmp_ge_u32_e32 vcc, v252, v249
	s_nop 1
	v_cndmask_b32_e32 v255, v255, v248, vcc
	v_add_u32_e32 v248, 1, v255
	v_mul_lo_u32 v254, v248, v249
	v_add_u32_e32 v253, 1, v253
	s_nop 0
	v_readfirstlane_b32 s100, v254
	v_cmp_eq_u32_e32 vcc, v253, v254
	s_cbranch_vccz .Lx3_poll
	v_mov_b32_e32 v248, 0x3400
	v_mov_b32_e32 v252, 1
	global_atomic_add v248, v252, s[76:77]
	v_add_u32_e32 v248, 0x1000, v251
	global_atomic_add v248, v252, s[76:77]
	s_branch .Lx3_go
.Lx3_poll:
	s_mov_b32 s101, 0
.Lx3_loop:
	global_load_dword v252, v251, s[76:77] sc1
	s_waitcnt vmcnt(0)
	v_readfirstlane_b32 s98, v252
	s_cmp_ge_u32 s98, s100
	s_cbranch_scc1 .Lx3_go
	s_sleep 1
	s_add_i32 s101, s101, 1
	s_cmp_lt_u32 s101, 0x100000
	s_cbranch_scc1 .Lx3_loop
.Lx3_go:
	buffer_inv sc1
	s_waitcnt vmcnt(0)
	s_branch .LBB0_639
.Lx3_full:
	s_add_i32 s0, 0, 0x23e20
	v_mov_b32_e32 v2, s0
	s_waitcnt vmcnt(0) expcnt(0) lgkmcnt(0)
	ds_read_b32 v4, v2
	s_add_i32 s0, 0, 0x23e24
	v_mov_b32_e32 v2, s0
	ds_read_b32 v2, v2
	s_waitcnt lgkmcnt(1)
	v_cmp_ne_u32_e32 vcc, 0, v4
	s_cbranch_vccnz .LBB0_603
	s_add_u32 s6, s76, 0x1000
	s_load_dwordx2 s[0:1], s[86:87], 0x4
	s_addc_u32 s7, s77, 0
	s_add_u32 s8, s76, 0x1100
	s_addc_u32 s9, s77, 0
	s_add_u32 s10, s76, 0x1200
	s_addc_u32 s11, s77, 0
	s_waitcnt lgkmcnt(0)
	s_mul_i32 s0, s0, s79
	s_add_u32 s12, s76, 0x1300
	s_mul_i32 s0, s0, s1
	s_addc_u32 s13, s77, 0
	s_mov_b32 s1, 1
	v_mov_b32_e32 v18, 0
	s_branch .LBB0_591
